# sum_partials (phase 21 and phase 3) rewritten: all 32 partials requested together
# speedup vs baseline: 1.0205x; 1.0022x over previous
.LBB0_77:
	v_readlane_b32 s28, v253, 47
	v_readlane_b32 s36, v251, 28
	v_readlane_b32 s93, v250, 12
	v_readlane_b32 s29, v253, 48
	s_mov_b64 s[68:69], s[96:97]
	s_cmp_lt_i32 s86, 11
	s_mov_b64 s[0:1], -1
	v_readlane_b32 s37, v251, 29
	s_cbranch_scc1 .LBB0_300
	s_cmp_lt_i32 s86, 16
	s_cbranch_scc1 .LBB0_181
	s_cmp_lt_i32 s86, 19
	s_cbranch_scc1 .LBB0_116
	s_cmp_lt_i32 s86, 20
	s_cbranch_scc1 .LBB0_98
	s_cmp_lt_i32 s86, 21
	s_cbranch_scc1 .LBB0_92
	s_cmp_eq_u32 s86, 21
	s_cbranch_scc0 .LBB0_91
	s_waitcnt vmcnt(0)
	v_mov_b32_e32 v0, v163
	v_readlane_b32 s0, v250, 4
	s_nop 1
	v_add_u32_e32 v8, s0, v0
	s_movk_i32 s0, 0x3c00
	v_cmp_gt_i32_e32 vcc, s0, v8
	s_and_saveexec_b64 s[0:1], vcc
	v_readlane_b32 s12, v249, 12
	v_readlane_b32 s13, v249, 13
	v_readlane_b32 s14, v249, 14
	v_readlane_b32 s15, v249, 15
	v_readlane_b32 s16, v249, 16
	v_readlane_b32 s17, v249, 17
	v_readlane_b32 s18, v249, 18
	v_readlane_b32 s19, v249, 19
	s_cbranch_execz .LBB0_90
	v_readlane_b32 s4, v249, 14
	v_readlane_b32 s5, v249, 15
	v_readfirstlane_b32 s2, v8
	v_readlane_b32 s3, v255, 2
	v_and_b32_e32 v129, 63, v163
	v_lshlrev_b32_e32 v129, 4, v129
.Lsump_p21_item:
	s_lshl_b32 s16, s2, 4
	s_add_u32 s12, s16, 0x700000
	s_add_u32 s12, s4, s12
	s_addc_u32 s13, s5, 0
	s_add_u32 s14, s16, 0x0
	s_add_u32 s14, s4, s14
	s_addc_u32 s15, s5, 0
	v_mov_b32_e32 v128, v129
	global_load_dwordx4 v[0:3], v128, s[12:13]
	v_add_u32_e32 v128, 0x3c000, v128
	global_load_dwordx4 v[4:7], v128, s[12:13]
	v_add_u32_e32 v128, 0x3c000, v128
	global_load_dwordx4 v[8:11], v128, s[12:13]
	v_add_u32_e32 v128, 0x3c000, v128
	global_load_dwordx4 v[12:15], v128, s[12:13]
	v_add_u32_e32 v128, 0x3c000, v128
	global_load_dwordx4 v[16:19], v128, s[12:13]
	v_add_u32_e32 v128, 0x3c000, v128
	global_load_dwordx4 v[20:23], v128, s[12:13]
	v_add_u32_e32 v128, 0x3c000, v128
	global_load_dwordx4 v[24:27], v128, s[12:13]
	v_add_u32_e32 v128, 0x3c000, v128
	global_load_dwordx4 v[28:31], v128, s[12:13]
	v_add_u32_e32 v128, 0x3c000, v128
	global_load_dwordx4 v[32:35], v128, s[12:13]
	v_add_u32_e32 v128, 0x3c000, v128
	global_load_dwordx4 v[36:39], v128, s[12:13]
	v_add_u32_e32 v128, 0x3c000, v128
	global_load_dwordx4 v[40:43], v128, s[12:13]
	v_add_u32_e32 v128, 0x3c000, v128
	global_load_dwordx4 v[44:47], v128, s[12:13]
	v_add_u32_e32 v128, 0x3c000, v128
	global_load_dwordx4 v[48:51], v128, s[12:13]
	v_add_u32_e32 v128, 0x3c000, v128
	global_load_dwordx4 v[52:55], v128, s[12:13]
	v_add_u32_e32 v128, 0x3c000, v128
	global_load_dwordx4 v[56:59], v128, s[12:13]
	v_add_u32_e32 v128, 0x3c000, v128
	global_load_dwordx4 v[60:63], v128, s[12:13]
	v_add_u32_e32 v128, 0x3c000, v128
	global_load_dwordx4 v[64:67], v128, s[12:13]
	v_add_u32_e32 v128, 0x3c000, v128
	global_load_dwordx4 v[68:71], v128, s[12:13]
	v_add_u32_e32 v128, 0x3c000, v128
	global_load_dwordx4 v[72:75], v128, s[12:13]
	v_add_u32_e32 v128, 0x3c000, v128
	global_load_dwordx4 v[76:79], v128, s[12:13]
	v_add_u32_e32 v128, 0x3c000, v128
	global_load_dwordx4 v[80:83], v128, s[12:13]
	v_add_u32_e32 v128, 0x3c000, v128
	global_load_dwordx4 v[84:87], v128, s[12:13]
	v_add_u32_e32 v128, 0x3c000, v128
	global_load_dwordx4 v[88:91], v128, s[12:13]
	v_add_u32_e32 v128, 0x3c000, v128
	global_load_dwordx4 v[92:95], v128, s[12:13]
	v_add_u32_e32 v128, 0x3c000, v128
	global_load_dwordx4 v[96:99], v128, s[12:13]
	v_add_u32_e32 v128, 0x3c000, v128
	global_load_dwordx4 v[100:103], v128, s[12:13]
	v_add_u32_e32 v128, 0x3c000, v128
	global_load_dwordx4 v[104:107], v128, s[12:13]
	v_add_u32_e32 v128, 0x3c000, v128
	global_load_dwordx4 v[108:111], v128, s[12:13]
	v_add_u32_e32 v128, 0x3c000, v128
	global_load_dwordx4 v[112:115], v128, s[12:13]
	v_add_u32_e32 v128, 0x3c000, v128
	global_load_dwordx4 v[116:119], v128, s[12:13]
	v_add_u32_e32 v128, 0x3c000, v128
	global_load_dwordx4 v[120:123], v128, s[12:13]
	v_add_u32_e32 v128, 0x3c000, v128
	global_load_dwordx4 v[124:127], v128, s[12:13]
	s_waitcnt vmcnt(30)
	v_pk_add_f32 v[0:1], v[0:1], v[4:5]
	v_pk_add_f32 v[2:3], v[2:3], v[6:7]
	s_waitcnt vmcnt(29)
	v_pk_add_f32 v[0:1], v[0:1], v[8:9]
	v_pk_add_f32 v[2:3], v[2:3], v[10:11]
	s_waitcnt vmcnt(28)
	v_pk_add_f32 v[0:1], v[0:1], v[12:13]
	v_pk_add_f32 v[2:3], v[2:3], v[14:15]
	s_waitcnt vmcnt(27)
	v_pk_add_f32 v[0:1], v[0:1], v[16:17]
	v_pk_add_f32 v[2:3], v[2:3], v[18:19]
	s_waitcnt vmcnt(26)
	v_pk_add_f32 v[0:1], v[0:1], v[20:21]
	v_pk_add_f32 v[2:3], v[2:3], v[22:23]
	s_waitcnt vmcnt(25)
	v_pk_add_f32 v[0:1], v[0:1], v[24:25]
	v_pk_add_f32 v[2:3], v[2:3], v[26:27]
	s_waitcnt vmcnt(24)
	v_pk_add_f32 v[0:1], v[0:1], v[28:29]
	v_pk_add_f32 v[2:3], v[2:3], v[30:31]
	s_waitcnt vmcnt(23)
	v_pk_add_f32 v[0:1], v[0:1], v[32:33]
	v_pk_add_f32 v[2:3], v[2:3], v[34:35]
	s_waitcnt vmcnt(22)
	v_pk_add_f32 v[0:1], v[0:1], v[36:37]
	v_pk_add_f32 v[2:3], v[2:3], v[38:39]
	s_waitcnt vmcnt(21)
	v_pk_add_f32 v[0:1], v[0:1], v[40:41]
	v_pk_add_f32 v[2:3], v[2:3], v[42:43]
	s_waitcnt vmcnt(20)
	v_pk_add_f32 v[0:1], v[0:1], v[44:45]
	v_pk_add_f32 v[2:3], v[2:3], v[46:47]
	s_waitcnt vmcnt(19)
	v_pk_add_f32 v[0:1], v[0:1], v[48:49]
	v_pk_add_f32 v[2:3], v[2:3], v[50:51]
	s_waitcnt vmcnt(18)
	v_pk_add_f32 v[0:1], v[0:1], v[52:53]
	v_pk_add_f32 v[2:3], v[2:3], v[54:55]
	s_waitcnt vmcnt(17)
	v_pk_add_f32 v[0:1], v[0:1], v[56:57]
	v_pk_add_f32 v[2:3], v[2:3], v[58:59]
	s_waitcnt vmcnt(16)
	v_pk_add_f32 v[0:1], v[0:1], v[60:61]
	v_pk_add_f32 v[2:3], v[2:3], v[62:63]
	s_waitcnt vmcnt(15)
	v_pk_add_f32 v[0:1], v[0:1], v[64:65]
	v_pk_add_f32 v[2:3], v[2:3], v[66:67]
	s_waitcnt vmcnt(14)
	v_pk_add_f32 v[0:1], v[0:1], v[68:69]
	v_pk_add_f32 v[2:3], v[2:3], v[70:71]
	s_waitcnt vmcnt(13)
	v_pk_add_f32 v[0:1], v[0:1], v[72:73]
	v_pk_add_f32 v[2:3], v[2:3], v[74:75]
	s_waitcnt vmcnt(12)
	v_pk_add_f32 v[0:1], v[0:1], v[76:77]
	v_pk_add_f32 v[2:3], v[2:3], v[78:79]
	s_waitcnt vmcnt(11)
	v_pk_add_f32 v[0:1], v[0:1], v[80:81]
	v_pk_add_f32 v[2:3], v[2:3], v[82:83]
	s_waitcnt vmcnt(10)
	v_pk_add_f32 v[0:1], v[0:1], v[84:85]
	v_pk_add_f32 v[2:3], v[2:3], v[86:87]
	s_waitcnt vmcnt(9)
	v_pk_add_f32 v[0:1], v[0:1], v[88:89]
	v_pk_add_f32 v[2:3], v[2:3], v[90:91]
	s_waitcnt vmcnt(8)
	v_pk_add_f32 v[0:1], v[0:1], v[92:93]
	v_pk_add_f32 v[2:3], v[2:3], v[94:95]
	s_waitcnt vmcnt(7)
	v_pk_add_f32 v[0:1], v[0:1], v[96:97]
	v_pk_add_f32 v[2:3], v[2:3], v[98:99]
	s_waitcnt vmcnt(6)
	v_pk_add_f32 v[0:1], v[0:1], v[100:101]
	v_pk_add_f32 v[2:3], v[2:3], v[102:103]
	s_waitcnt vmcnt(5)
	v_pk_add_f32 v[0:1], v[0:1], v[104:105]
	v_pk_add_f32 v[2:3], v[2:3], v[106:107]
	s_waitcnt vmcnt(4)
	v_pk_add_f32 v[0:1], v[0:1], v[108:109]
	v_pk_add_f32 v[2:3], v[2:3], v[110:111]
	s_waitcnt vmcnt(3)
	v_pk_add_f32 v[0:1], v[0:1], v[112:113]
	v_pk_add_f32 v[2:3], v[2:3], v[114:115]
	s_waitcnt vmcnt(2)
	v_pk_add_f32 v[0:1], v[0:1], v[116:117]
	v_pk_add_f32 v[2:3], v[2:3], v[118:119]
	s_waitcnt vmcnt(1)
	v_pk_add_f32 v[0:1], v[0:1], v[120:121]
	v_pk_add_f32 v[2:3], v[2:3], v[122:123]
	s_waitcnt vmcnt(0)
	v_pk_add_f32 v[0:1], v[0:1], v[124:125]
	v_pk_add_f32 v[2:3], v[2:3], v[126:127]
	global_store_dwordx4 v129, v[0:3], s[14:15]
	s_add_u32 s2, s2, s3
	s_cmp_lt_u32 s2, 0x3c00
	s_cbranch_scc1 .Lsump_p21_item

.LBB0_973:
	s_and_b64 vcc, exec, s[0:1]
	s_cbranch_vccz .LBB0_1025
	s_waitcnt vmcnt(0)
	v_mov_b32_e32 v0, v163
	v_readlane_b32 s0, v250, 4
	s_nop 1
	v_add_u32_e32 v8, s0, v0
	s_movk_i32 s0, 0x2c00
	v_cmp_gt_i32_e32 vcc, s0, v8
	s_and_saveexec_b64 s[0:1], vcc
	s_cbranch_execz .LBB0_981
	v_readlane_b32 s4, v249, 14
	v_readlane_b32 s5, v249, 15
	v_readfirstlane_b32 s2, v8
	v_readlane_b32 s3, v255, 2
	v_and_b32_e32 v129, 63, v163
	v_lshlrev_b32_e32 v129, 4, v129
.Lsump_p3_item:
	s_lshl_b32 s16, s2, 4
	s_add_u32 s12, s16, 0x1d800000
	s_add_u32 s12, s4, s12
	s_addc_u32 s13, s5, 0
	s_add_u32 s14, s16, 0xe80000
	s_add_u32 s14, s4, s14
	s_addc_u32 s15, s5, 0
	v_mov_b32_e32 v128, v129
	global_load_dwordx4 v[0:3], v128, s[12:13]
	v_add_u32_e32 v128, 0x2c000, v128
	global_load_dwordx4 v[4:7], v128, s[12:13]
	v_add_u32_e32 v128, 0x2c000, v128
	global_load_dwordx4 v[8:11], v128, s[12:13]
	v_add_u32_e32 v128, 0x2c000, v128
	global_load_dwordx4 v[12:15], v128, s[12:13]
	v_add_u32_e32 v128, 0x2c000, v128
	global_load_dwordx4 v[16:19], v128, s[12:13]
	v_add_u32_e32 v128, 0x2c000, v128
	global_load_dwordx4 v[20:23], v128, s[12:13]
	v_add_u32_e32 v128, 0x2c000, v128
	global_load_dwordx4 v[24:27], v128, s[12:13]
	v_add_u32_e32 v128, 0x2c000, v128
	global_load_dwordx4 v[28:31], v128, s[12:13]
	v_add_u32_e32 v128, 0x2c000, v128
	global_load_dwordx4 v[32:35], v128, s[12:13]
	v_add_u32_e32 v128, 0x2c000, v128
	global_load_dwordx4 v[36:39], v128, s[12:13]
	v_add_u32_e32 v128, 0x2c000, v128
	global_load_dwordx4 v[40:43], v128, s[12:13]
	v_add_u32_e32 v128, 0x2c000, v128
	global_load_dwordx4 v[44:47], v128, s[12:13]
	v_add_u32_e32 v128, 0x2c000, v128
	global_load_dwordx4 v[48:51], v128, s[12:13]
	v_add_u32_e32 v128, 0x2c000, v128
	global_load_dwordx4 v[52:55], v128, s[12:13]
	v_add_u32_e32 v128, 0x2c000, v128
	global_load_dwordx4 v[56:59], v128, s[12:13]
	v_add_u32_e32 v128, 0x2c000, v128
	global_load_dwordx4 v[60:63], v128, s[12:13]
	v_add_u32_e32 v128, 0x2c000, v128
	global_load_dwordx4 v[64:67], v128, s[12:13]
	v_add_u32_e32 v128, 0x2c000, v128
	global_load_dwordx4 v[68:71], v128, s[12:13]
	v_add_u32_e32 v128, 0x2c000, v128
	global_load_dwordx4 v[72:75], v128, s[12:13]
	v_add_u32_e32 v128, 0x2c000, v128
	global_load_dwordx4 v[76:79], v128, s[12:13]
	v_add_u32_e32 v128, 0x2c000, v128
	global_load_dwordx4 v[80:83], v128, s[12:13]
	v_add_u32_e32 v128, 0x2c000, v128
	global_load_dwordx4 v[84:87], v128, s[12:13]
	v_add_u32_e32 v128, 0x2c000, v128
	global_load_dwordx4 v[88:91], v128, s[12:13]
	v_add_u32_e32 v128, 0x2c000, v128
	global_load_dwordx4 v[92:95], v128, s[12:13]
	v_add_u32_e32 v128, 0x2c000, v128
	global_load_dwordx4 v[96:99], v128, s[12:13]
	v_add_u32_e32 v128, 0x2c000, v128
	global_load_dwordx4 v[100:103], v128, s[12:13]
	v_add_u32_e32 v128, 0x2c000, v128
	global_load_dwordx4 v[104:107], v128, s[12:13]
	v_add_u32_e32 v128, 0x2c000, v128
	global_load_dwordx4 v[108:111], v128, s[12:13]
	v_add_u32_e32 v128, 0x2c000, v128
	global_load_dwordx4 v[112:115], v128, s[12:13]
	v_add_u32_e32 v128, 0x2c000, v128
	global_load_dwordx4 v[116:119], v128, s[12:13]
	v_add_u32_e32 v128, 0x2c000, v128
	global_load_dwordx4 v[120:123], v128, s[12:13]
	v_add_u32_e32 v128, 0x2c000, v128
	global_load_dwordx4 v[124:127], v128, s[12:13]
	s_waitcnt vmcnt(30)
	v_pk_add_f32 v[0:1], v[0:1], v[4:5]
	v_pk_add_f32 v[2:3], v[2:3], v[6:7]
	s_waitcnt vmcnt(29)
	v_pk_add_f32 v[0:1], v[0:1], v[8:9]
	v_pk_add_f32 v[2:3], v[2:3], v[10:11]
	s_waitcnt vmcnt(28)
	v_pk_add_f32 v[0:1], v[0:1], v[12:13]
	v_pk_add_f32 v[2:3], v[2:3], v[14:15]
	s_waitcnt vmcnt(27)
	v_pk_add_f32 v[0:1], v[0:1], v[16:17]
	v_pk_add_f32 v[2:3], v[2:3], v[18:19]
	s_waitcnt vmcnt(26)
	v_pk_add_f32 v[0:1], v[0:1], v[20:21]
	v_pk_add_f32 v[2:3], v[2:3], v[22:23]
	s_waitcnt vmcnt(25)
	v_pk_add_f32 v[0:1], v[0:1], v[24:25]
	v_pk_add_f32 v[2:3], v[2:3], v[26:27]
	s_waitcnt vmcnt(24)
	v_pk_add_f32 v[0:1], v[0:1], v[28:29]
	v_pk_add_f32 v[2:3], v[2:3], v[30:31]
	s_waitcnt vmcnt(23)
	v_pk_add_f32 v[0:1], v[0:1], v[32:33]
	v_pk_add_f32 v[2:3], v[2:3], v[34:35]
	s_waitcnt vmcnt(22)
	v_pk_add_f32 v[0:1], v[0:1], v[36:37]
	v_pk_add_f32 v[2:3], v[2:3], v[38:39]
	s_waitcnt vmcnt(21)
	v_pk_add_f32 v[0:1], v[0:1], v[40:41]
	v_pk_add_f32 v[2:3], v[2:3], v[42:43]
	s_waitcnt vmcnt(20)
	v_pk_add_f32 v[0:1], v[0:1], v[44:45]
	v_pk_add_f32 v[2:3], v[2:3], v[46:47]
	s_waitcnt vmcnt(19)
	v_pk_add_f32 v[0:1], v[0:1], v[48:49]
	v_pk_add_f32 v[2:3], v[2:3], v[50:51]
	s_waitcnt vmcnt(18)
	v_pk_add_f32 v[0:1], v[0:1], v[52:53]
	v_pk_add_f32 v[2:3], v[2:3], v[54:55]
	s_waitcnt vmcnt(17)
	v_pk_add_f32 v[0:1], v[0:1], v[56:57]
	v_pk_add_f32 v[2:3], v[2:3], v[58:59]
	s_waitcnt vmcnt(16)
	v_pk_add_f32 v[0:1], v[0:1], v[60:61]
	v_pk_add_f32 v[2:3], v[2:3], v[62:63]
	s_waitcnt vmcnt(15)
	v_pk_add_f32 v[0:1], v[0:1], v[64:65]
	v_pk_add_f32 v[2:3], v[2:3], v[66:67]
	s_waitcnt vmcnt(14)
	v_pk_add_f32 v[0:1], v[0:1], v[68:69]
	v_pk_add_f32 v[2:3], v[2:3], v[70:71]
	s_waitcnt vmcnt(13)
	v_pk_add_f32 v[0:1], v[0:1], v[72:73]
	v_pk_add_f32 v[2:3], v[2:3], v[74:75]
	s_waitcnt vmcnt(12)
	v_pk_add_f32 v[0:1], v[0:1], v[76:77]
	v_pk_add_f32 v[2:3], v[2:3], v[78:79]
	s_waitcnt vmcnt(11)
	v_pk_add_f32 v[0:1], v[0:1], v[80:81]
	v_pk_add_f32 v[2:3], v[2:3], v[82:83]
	s_waitcnt vmcnt(10)
	v_pk_add_f32 v[0:1], v[0:1], v[84:85]
	v_pk_add_f32 v[2:3], v[2:3], v[86:87]
	s_waitcnt vmcnt(9)
	v_pk_add_f32 v[0:1], v[0:1], v[88:89]
	v_pk_add_f32 v[2:3], v[2:3], v[90:91]
	s_waitcnt vmcnt(8)
	v_pk_add_f32 v[0:1], v[0:1], v[92:93]
	v_pk_add_f32 v[2:3], v[2:3], v[94:95]
	s_waitcnt vmcnt(7)
	v_pk_add_f32 v[0:1], v[0:1], v[96:97]
	v_pk_add_f32 v[2:3], v[2:3], v[98:99]
	s_waitcnt vmcnt(6)
	v_pk_add_f32 v[0:1], v[0:1], v[100:101]
	v_pk_add_f32 v[2:3], v[2:3], v[102:103]
	s_waitcnt vmcnt(5)
	v_pk_add_f32 v[0:1], v[0:1], v[104:105]
	v_pk_add_f32 v[2:3], v[2:3], v[106:107]
	s_waitcnt vmcnt(4)
	v_pk_add_f32 v[0:1], v[0:1], v[108:109]
	v_pk_add_f32 v[2:3], v[2:3], v[110:111]
	s_waitcnt vmcnt(3)
	v_pk_add_f32 v[0:1], v[0:1], v[112:113]
	v_pk_add_f32 v[2:3], v[2:3], v[114:115]
	s_waitcnt vmcnt(2)
	v_pk_add_f32 v[0:1], v[0:1], v[116:117]
	v_pk_add_f32 v[2:3], v[2:3], v[118:119]
	s_waitcnt vmcnt(1)
	v_pk_add_f32 v[0:1], v[0:1], v[120:121]
	v_pk_add_f32 v[2:3], v[2:3], v[122:123]
	s_waitcnt vmcnt(0)
	v_pk_add_f32 v[0:1], v[0:1], v[124:125]
	v_pk_add_f32 v[2:3], v[2:3], v[126:127]
	global_store_dwordx4 v129, v[0:3], s[14:15]
	s_add_u32 s2, s2, s3
	s_cmp_lt_u32 s2, 0x2c00
	s_cbranch_scc1 .Lsump_p3_item
